# k9
# speedup vs baseline: 1.0072x; 1.0072x over previous
; __device__ __forceinline__ void mirror_phase(u16* __restrict__ F, const float* __restrict__ alt, const float* __restrict__ E, unsigned sx, unsigned srank, unsigned snloc) {
;     ...
;   for (int li = (int)srank * NTHREADS + tid; li < DM; li += (int)snloc * NTHREADS) {
;     const int idx = (int)sx * DM + li;
;     float s = E[idx];
; #pragma unroll 8
;     for (int q = 0; q < 64; ++q) s += alt[(size_t)q * (NBATCH * DM) + idx];
;     const int b = idx >> 10, n = idx & 1023;
;     F[((size_t)b * SEQ + 2048) * DM + n] = f2bf(s * (1.0f / 1024.0f));
;   }
.LBB0_510:
	v_lshl_add_u64 v[6:7], v[0:1], 0, s[12:13]
	s_add_u32 s12, s12, 0x40000
	s_addc_u32 s13, s13, 0
	s_mov_b32 s3, 0
	s_mov_b32 s2, 0x4000000
	v_lshl_add_u64 v[8:9], v[6:7], 0, s[2:3]
	global_load_dword v20, v[8:9], off
	s_mov_b32 s2, 0x4008000
	v_lshl_add_u64 v[8:9], v[6:7], 0, s[2:3]
	global_load_dword v21, v[8:9], off
	s_mov_b32 s2, 0x4010000
	v_lshl_add_u64 v[8:9], v[6:7], 0, s[2:3]
	global_load_dword v22, v[8:9], off
	s_mov_b32 s2, 0x4018000
	v_lshl_add_u64 v[8:9], v[6:7], 0, s[2:3]
	global_load_dword v23, v[8:9], off
	s_mov_b32 s2, 0x4020000
	v_lshl_add_u64 v[8:9], v[6:7], 0, s[2:3]
	global_load_dword v24, v[8:9], off
	s_mov_b32 s2, 0x4028000
	v_lshl_add_u64 v[8:9], v[6:7], 0, s[2:3]
	global_load_dword v25, v[8:9], off
	s_mov_b32 s2, 0x4030000
	v_lshl_add_u64 v[8:9], v[6:7], 0, s[2:3]
	global_load_dword v26, v[8:9], off
	s_mov_b32 s2, 0x4038000
	v_lshl_add_u64 v[8:9], v[6:7], 0, s[2:3]
	global_load_dword v27, v[8:9], off
	s_cmp_eq_u32 s12, 0x200000
	s_waitcnt vmcnt(7)
	v_add_f32_e32 v3, v3, v20
	s_waitcnt vmcnt(6)
	v_add_f32_e32 v3, v3, v21
	s_waitcnt vmcnt(5)
	v_add_f32_e32 v3, v3, v22
	s_waitcnt vmcnt(4)
	v_add_f32_e32 v3, v3, v23
	s_waitcnt vmcnt(3)
	v_add_f32_e32 v3, v3, v24
	s_waitcnt vmcnt(2)
	v_add_f32_e32 v3, v3, v25
	s_waitcnt vmcnt(1)
	v_add_f32_e32 v3, v3, v26
	s_waitcnt vmcnt(0)
	v_add_f32_e32 v3, v3, v27
	s_cbranch_scc0 .LBB0_510
	v_mul_f32_e32 v3, 0x3a800000, v3
	v_ashrrev_i32_e32 v2, 10, v2
	v_bfe_u32 v6, v3, 16, 1
	v_add3_u32 v6, v3, v6, s74
	v_ashrrev_i32_e32 v3, 31, v2
	v_and_b32_e32 v5, 0x3ff, v4
	v_lshlrev_b64 v[2:3], 23, v[2:3]
	v_lshl_add_u64 v[2:3], s[6:7], 0, v[2:3]
	v_lshlrev_b32_e32 v176, 1, v5
	v_lshl_add_u64 v[2:3], v[2:3], 0, v[176:177]
	v_readlane_b32 s2, v238, 50
	v_add_co_u32_e32 v2, vcc, 0x400000, v2
	v_readlane_b32 s3, v238, 51
	s_nop 0
	v_addc_co_u32_e32 v3, vcc, 0, v3, vcc
	v_add_u32_e32 v4, s2, v4
	s_movk_i32 s0, 0x3ff
	v_readlane_b32 s2, v238, 52
	v_cmp_lt_i32_e32 vcc, s0, v4
	v_readlane_b32 s3, v238, 53
	s_or_b64 s[10:11], vcc, s[10:11]
	global_store_short_d16_hi v[2:3], v6, off
	v_lshl_add_u64 v[0:1], v[0:1], 0, s[2:3]
	s_andn2_b64 exec, exec, s[10:11]
	s_cbranch_execnz .LBB0_509

; __device__ __forceinline__ void partialSM(f32x16& p0, f32x16& p1, float& m_reg, float& mn, float& alpha) {
;   constexpr float C = ASCALE * 1.4426950408889634f;
;   float pmax = p0[0]; for (int r = 1; r < 16; ++r) pmax = fmaxf(pmax, p0[r]); for (int r = 0; r < 16; ++r) pmax = fmaxf(pmax, p1[r]);
;   { auto rr = __builtin_amdgcn_permlane32_swap(__float_as_uint(pmax), __float_as_uint(pmax), false, false);
;     pmax = fmaxf(__uint_as_float(rr[0]), __uint_as_float(rr[1])); }
;   if (__builtin_expect(__all(pmax - m_reg <= ATHR / ASCALE), 1)) { mn = m_reg; alpha = 1.f; }
;   else { mn = fmaxf(m_reg, pmax); alpha = __builtin_amdgcn_exp2f((m_reg - mn) * C); m_reg = mn; }
;   float mnC = -mn * C;
;   for (int r = 0; r < 16; ++r) p0[r] = fmaf(p0[r], C, mnC); for (int r = 0; r < 16; ++r) p1[r] = fmaf(p1[r], C, mnC);
;   for (int r = 0; r < 16; ++r) p0[r] = __builtin_amdgcn_exp2f(p0[r]);
; }
; __device__ __forceinline__ void finishSM(f32x16& p0, f32x16& p1, float alpha, float& l_reg, bf16x8& pa0, bf16x8& pa1, bf16x8& pa2, bf16x8& pa3) {
;   for (int r = 0; r < 16; ++r) p1[r] = __builtin_amdgcn_exp2f(p1[r]);
;   float ps = 0; for (int r = 0; r < 16; ++r) ps += p0[r]; for (int r = 0; r < 16; ++r) ps += p1[r];
;   { auto rr = __builtin_amdgcn_permlane32_swap(__float_as_uint(ps), __float_as_uint(ps), false, false);
;     ps = __uint_as_float(rr[0]) + __uint_as_float(rr[1]); }
;   l_reg = l_reg * alpha + ps;
;     ...
;   PK4(p0, 0, pa0); PK4(p0, 8, pa1); PK4(p1, 0, pa2); PK4(p1, 8, pa3);
;     ...
; }
; __device__ __forceinline__ void qkt(f32x16& p0, f32x16& p1, const u16* Ks, const bf16x8* qr, int r32, int hi) {
;   p0 = f32x16{}; p1 = f32x16{};
;   for (int d0 = 0; d0 < 8; ++d0) { int cb = (d0 * 16 + hi * 8) * 2;
;     bf16x8 b0 = *reinterpret_cast<const bf16x8*>((const char*)Ks + KSWZ(r32, cb));
;     bf16x8 b1 = *reinterpret_cast<const bf16x8*>((const char*)Ks + KSWZ(32 + r32, cb));
;     p0 = __builtin_amdgcn_mfma_f32_32x32x16_bf16(b0, qr[d0], p0, 0, 0, 0);
;     p1 = __builtin_amdgcn_mfma_f32_32x32x16_bf16(b1, qr[d0], p1, 0, 0, 0); }
; }
; __device__ __forceinline__ int v_st(int k, int c) { const int kk = (k & ~0xC) | ((k & 4) << 1) | ((k & 8) >> 1); return ((kk >> 3) * 4 + (c >> 5)) * 512 + ((kk & 7) * 32 + (c & 31)) * 2; }
.LBB0_864:
	ds_read_b64_tr_b16 v[216:217], v195 offset:0
	ds_read_b64_tr_b16 v[218:219], v195 offset:0x800
	ds_read_b64_tr_b16 v[220:221], v195 offset:0x1000
	ds_read_b64_tr_b16 v[222:223], v195 offset:0x1800
	ds_read_b64_tr_b16 v[224:225], v195 offset:0x2000
	ds_read_b64_tr_b16 v[226:227], v195 offset:0x2800
	ds_read_b64_tr_b16 v[228:229], v195 offset:0x3000
	ds_read_b64_tr_b16 v[230:231], v195 offset:0x3800
	s_waitcnt lgkmcnt(0)
	s_nop 0
	v_mfma_f32_32x32x16_bf16 v[0:15], v[160:163], v[216:219], v[0:15]
	ds_read_b64_tr_b16 v[216:217], v195 offset:0x200
	ds_read_b64_tr_b16 v[218:219], v195 offset:0xa00
	v_mfma_f32_32x32x16_bf16 v[0:15], v[164:167], v[220:223], v[0:15]
	ds_read_b64_tr_b16 v[220:221], v195 offset:0x1200
	ds_read_b64_tr_b16 v[222:223], v195 offset:0x1a00
	v_mfma_f32_32x32x16_bf16 v[0:15], v[168:171], v[224:227], v[0:15]
	ds_read_b64_tr_b16 v[224:225], v195 offset:0x2200
	ds_read_b64_tr_b16 v[226:227], v195 offset:0x2a00
	v_mfma_f32_32x32x16_bf16 v[0:15], v[172:175], v[228:231], v[0:15]
	ds_read_b64_tr_b16 v[228:229], v195 offset:0x3200
	ds_read_b64_tr_b16 v[230:231], v195 offset:0x3a00
	s_waitcnt lgkmcnt(0)
	v_mfma_f32_32x32x16_bf16 v[48:63], v[160:163], v[216:219], v[48:63]
	ds_read_b64_tr_b16 v[216:217], v195 offset:0x400
	ds_read_b64_tr_b16 v[218:219], v195 offset:0xc00
	v_mfma_f32_32x32x16_bf16 v[48:63], v[164:167], v[220:223], v[48:63]
	ds_read_b64_tr_b16 v[220:221], v195 offset:0x1400
	ds_read_b64_tr_b16 v[222:223], v195 offset:0x1c00
	v_mfma_f32_32x32x16_bf16 v[48:63], v[168:171], v[224:227], v[48:63]
	ds_read_b64_tr_b16 v[224:225], v195 offset:0x2400
	ds_read_b64_tr_b16 v[226:227], v195 offset:0x2c00
	v_mfma_f32_32x32x16_bf16 v[48:63], v[172:175], v[228:231], v[48:63]
	ds_read_b64_tr_b16 v[228:229], v195 offset:0x3400
	ds_read_b64_tr_b16 v[230:231], v195 offset:0x3c00
	s_waitcnt lgkmcnt(0)
	v_mfma_f32_32x32x16_bf16 v[32:47], v[160:163], v[216:219], v[32:47]
	ds_read_b64_tr_b16 v[216:217], v195 offset:0x600
	ds_read_b64_tr_b16 v[218:219], v195 offset:0xe00
	v_mfma_f32_32x32x16_bf16 v[32:47], v[164:167], v[220:223], v[32:47]
	ds_read_b64_tr_b16 v[220:221], v195 offset:0x1600
	ds_read_b64_tr_b16 v[222:223], v195 offset:0x1e00
	v_mfma_f32_32x32x16_bf16 v[32:47], v[168:171], v[224:227], v[32:47]
	ds_read_b64_tr_b16 v[224:225], v195 offset:0x2600
	ds_read_b64_tr_b16 v[226:227], v195 offset:0x2e00
	v_mfma_f32_32x32x16_bf16 v[32:47], v[172:175], v[228:231], v[32:47]
	ds_read_b64_tr_b16 v[228:229], v195 offset:0x3600
	ds_read_b64_tr_b16 v[230:231], v195 offset:0x3e00
	s_waitcnt lgkmcnt(0)
	v_mfma_f32_32x32x16_bf16 v[16:31], v[160:163], v[216:219], v[16:31]
	v_max_f32_e32 v160, v81, v81
	v_max_f32_e32 v161, v80, v80
	v_max_f32_e32 v160, v161, v160
	v_max3_f32 v160, v160, v82, v83
	v_max3_f32 v160, v160, v84, v85
	v_max3_f32 v160, v160, v86, v87
	v_max3_f32 v160, v160, v88, v89
	v_max3_f32 v160, v160, v90, v91
	v_max3_f32 v160, v160, v92, v93
	v_mfma_f32_32x32x16_bf16 v[16:31], v[164:167], v[220:223], v[16:31]
	v_max3_f32 v160, v160, v94, v95
	v_max3_f32 v160, v160, v64, v65
	v_max3_f32 v160, v160, v66, v67
	v_max3_f32 v160, v160, v68, v69
	v_max3_f32 v160, v160, v70, v71
	v_max3_f32 v160, v160, v72, v73
	v_max3_f32 v160, v160, v74, v75
	v_max3_f32 v160, v160, v76, v77
	v_mfma_f32_32x32x16_bf16 v[16:31], v[168:171], v[224:227], v[16:31]
	v_max3_f32 v160, v160, v78, v79
	v_mov_b32_e32 v161, v160
	s_nop 1
	v_permlane32_swap_b32_e32 v160, v161
	v_max_f32_e32 v161, v161, v161
	v_max_f32_e32 v160, v160, v160
	v_max_f32_e32 v160, v160, v161
	v_sub_f32_e32 v161, v160, v213
	v_cmp_ge_f32_e32 vcc, s56, v161
	v_max_f32_e32 v161, v213, v213
	v_max_f32_e32 v161, v161, v160
	v_mfma_f32_32x32x16_bf16 v[16:31], v[172:175], v[228:231], v[16:31]
	v_sub_f32_e32 v160, v213, v161
	v_mul_f32_e32 v160, 0x3e0293ee, v160
	v_exp_f32_e32 v160, v160
	s_cmp_eq_u64 vcc, exec
	s_cselect_b64 s[10:11], -1, 0
	s_barrier
	s_waitcnt vmcnt(4)
	v_cndmask_b32_e64 v160, v160, 1.0, s[10:11]
	v_cmp_gt_f32_e32 vcc, 1.0, v160
	s_cmp_eq_u64 s[24:25], 0
	s_cbranch_scc1 .Lattn_lw
	s_waitcnt vmcnt(0)
.Lattn_lw:
	ds_write_b128 v197, v[144:147] offset:16384
	ds_write_b128 v198, v[156:159] offset:16384
	ds_write_b128 v199, v[148:151] offset:49152
	ds_write_b128 v200, v[152:155] offset:49152
	s_cbranch_vccz .LBB0_868
	s_and_saveexec_b64 s[4:5], s[8:9]
	ds_write_b32 v193, v160 offset:128
	s_or_b64 exec, exec, s[4:5]
	s_waitcnt lgkmcnt(0)
	v_add_u32_e32 v156, v179, v176
	ds_read_b128 v[144:147], v156 offset:224
	ds_read_b128 v[148:151], v156 offset:192
	ds_read_b128 v[152:155], v156 offset:160
	ds_read_b128 v[156:159], v156 offset:128
	s_waitcnt lgkmcnt(3)
	v_pk_mul_f32 v[12:13], v[12:13], v[144:145]
	s_waitcnt lgkmcnt(2)
	v_pk_mul_f32 v[8:9], v[8:9], v[148:149]
	s_waitcnt lgkmcnt(1)
	v_pk_mul_f32 v[4:5], v[4:5], v[152:153]
	v_pk_mul_f32 v[14:15], v[14:15], v[146:147]
	v_pk_mul_f32 v[10:11], v[10:11], v[150:151]
	v_pk_mul_f32 v[6:7], v[6:7], v[154:155]
	s_waitcnt lgkmcnt(0)
	v_pk_mul_f32 v[2:3], v[2:3], v[158:159]
	v_pk_mul_f32 v[0:1], v[0:1], v[156:157]
	v_pk_mul_f32 v[60:61], v[60:61], v[144:145]
	v_pk_mul_f32 v[56:57], v[56:57], v[148:149]
	v_pk_mul_f32 v[52:53], v[52:53], v[152:153]
	v_pk_mul_f32 v[62:63], v[62:63], v[146:147]
	v_pk_mul_f32 v[58:59], v[58:59], v[150:151]
	v_pk_mul_f32 v[54:55], v[54:55], v[154:155]
	v_pk_mul_f32 v[50:51], v[50:51], v[158:159]
	v_pk_mul_f32 v[48:49], v[48:49], v[156:157]
	v_pk_mul_f32 v[44:45], v[44:45], v[144:145]
	v_pk_mul_f32 v[40:41], v[40:41], v[148:149]
	v_pk_mul_f32 v[36:37], v[36:37], v[152:153]
	v_pk_mul_f32 v[46:47], v[46:47], v[146:147]
	v_pk_mul_f32 v[42:43], v[42:43], v[150:151]
	v_pk_mul_f32 v[38:39], v[38:39], v[154:155]
	v_pk_mul_f32 v[34:35], v[34:35], v[158:159]
	v_pk_mul_f32 v[32:33], v[32:33], v[156:157]
	v_pk_mul_f32 v[28:29], v[28:29], v[144:145]
	v_pk_mul_f32 v[24:25], v[24:25], v[148:149]
	v_pk_mul_f32 v[20:21], v[20:21], v[152:153]
	v_pk_mul_f32 v[30:31], v[30:31], v[146:147]
	v_pk_mul_f32 v[26:27], v[26:27], v[150:151]
	v_pk_mul_f32 v[22:23], v[22:23], v[154:155]
	v_pk_mul_f32 v[18:19], v[18:19], v[158:159]
	v_pk_mul_f32 v[16:17], v[16:17], v[156:157]
